# P0 weight-transpose items redistributed: the 192 workgroups that also run an adaLN GEMV task take one item per wave, the 64 idle ones take four
# baseline (speedup 1.0000x reference)
; #define LAS __attribute__((address_space(3)))
; __global__ void __launch_bounds__(NTHR, 2) hybrid_fwd(Args a) {
;     ...
;         const bool split0 = IN(1);
;         if (split0) xcd_barrier_arrive(xbar);
;         LAS float* scr = (LAS float*)(lds + wave * 16384);
;         constexpr int I_AB = (D / 64) * (IN_AB / 32), I_OAB = (2048 / 64) * (D / 32), I_C = (D / 64) * (IN_C / 32), I_OC = (D / 64) * (D / 32);
;         for (int it = gw; it < I_AB; it += NGW) p0_transpose_item<1>(a.w_in_ab, D, IN_AB, WAB, scr, it, lane);
;         if (split0) xcd_barrier_wait(xbar, 0u);
.LBB0_46:
	s_mov_b32 s100, s34
	s_mov_b32 s101, s66
	s_cmp_lg_u32 s3, 0x100
	s_cbranch_scc1 .Lp0b_dist_done
	s_lshl_b32 s100, s2, 3
	s_add_i32 s100, s100, s79
	s_movk_i32 s101, 0x1000
	s_cmpk_lt_i32 s2, 0xc0
	s_cbranch_scc1 .Lp0b_dist_done
	s_movk_i32 s101, 0x200
.Lp0b_dist_done:
	s_cmpk_gt_i32 s100, 0xdff
	s_cbranch_scc1 .LBB0_77
	v_and_b32_e32 v1, 31, v0
	s_lshl_b32 s4, s79, 14
	v_lshlrev_b32_e32 v4, 2, v1
	v_lshlrev_b32_e32 v1, 3, v0
	s_add_i32 s4, s4, 0
	v_mov_b32_e32 v5, 0
	v_lshrrev_b32_e32 v9, 3, v154
	v_and_b32_e32 v1, 56, v1
	v_lshrrev_b32_e32 v2, 5, v154
	v_lshl_add_u64 v[6:7], s[26:27], 0, v[4:5]
	v_add_u32_e32 v8, s4, v4
	v_mul_u32_u24_e32 v3, 0x84, v1
	v_lshlrev_b32_e32 v4, 1, v1
	v_lshlrev_b32_e32 v1, 2, v9
	s_movk_i32 s12, 0x84
	v_lshl_add_u64 v[10:11], s[62:63], 0, v[4:5]
	v_add3_u32 v14, s4, v3, v1
	v_or_b32_e32 v15, 8, v9
	v_or_b32_e32 v16, 16, v9
	v_or_b32_e32 v17, 24, v9
	v_mov_b32_e32 v1, v2
	s_movk_i32 s13, 0x7000
	s_mov_b32 s14, s100

; #define LAS __attribute__((address_space(3)))
; __device__ __forceinline__ unsigned cvt_pk_bf16(float lo, float hi) { f32x2_t v = {lo, hi}; bf16x2_t b = __builtin_convertvector(v, bf16x2_t); return __builtin_bit_cast(unsigned, b); }
; template <int MODE>
; __device__ __forceinline__ void p0_transpose_item(const float* W, int K, int N, bf16_t* WT, LAS float* scr, int item, int lane) {
;     const int nblk = N / 32, kb = item / nblk, nb = item % nblk, k0 = 64 * kb, n0 = 32 * nb;
;     const int rb = MODE == 1 ? ab_row(n0) : (MODE == 2 ? c_row(n0) : n0);
; #pragma unroll 8
;     for (int i = 0; i < 32; ++i) { const int kk = 2 * i + (lane >> 5); scr[kk * 33 + (lane & 31)] = W[(size_t)(k0 + kk) * N + n0 + (lane & 31)]; }
;     asm volatile("s_waitcnt lgkmcnt(0)" ::: "memory");
;     const int c = lane & 7;
; #pragma unroll
;     for (int j = 0; j < 4; ++j) { const int n = (lane >> 3) + 8 * j; const LAS float* s = scr + (8 * c) * 33 + n;
;         u32x4 o; o.x = cvt_pk_bf16(s[0 * 33], s[1 * 33]); o.y = cvt_pk_bf16(s[2 * 33], s[3 * 33]); o.z = cvt_pk_bf16(s[4 * 33], s[5 * 33]); o.w = cvt_pk_bf16(s[6 * 33], s[7 * 33]);
;         *(u32x4*)(WT + (size_t)(rb + n) * K + k0 + 8 * c) = o; }
;     asm volatile("s_waitcnt lgkmcnt(0)" ::: "memory");
; }
; __global__ void __launch_bounds__(NTHR, 2) hybrid_fwd(Args a) {
;     ...
;         for (int it = gw; it < I_AB; it += NGW) p0_transpose_item<1>(a.w_in_ab, D, IN_AB, WAB, scr, it, lane);
.LBB0_75:
	s_lshl_b32 s10, s5, 1
	s_lshl_b32 s11, s6, 1
	v_or_b32_e32 v18, s11, v4
	s_add_i32 s18, s10, 4
	s_add_i32 s19, s11, 4
	s_add_i32 s22, s10, 8
	s_add_i32 s23, s11, 8
	s_add_i32 s24, s10, 12
	s_add_i32 s25, s11, 12
	s_add_i32 s26, s10, 16
	s_add_i32 s27, s11, 16
	s_add_i32 s35, s10, 20
	s_add_i32 s36, s11, 20
	s_add_i32 s37, s10, 24
	s_add_i32 s56, s11, 24
	s_add_i32 s57, s10, 28
	s_add_i32 s58, s11, 28
	v_or_b32_e32 v20, s10, v3
	v_mad_i64_i32 v[18:19], s[8:9], v18, s13, v[12:13]
	v_or_b32_e32 v24, s18, v3
	v_or_b32_e32 v22, s19, v4
	v_or_b32_e32 v28, s22, v3
	v_or_b32_e32 v26, s23, v4
	v_or_b32_e32 v32, s24, v3
	v_or_b32_e32 v30, s25, v4
	v_or_b32_e32 v36, s26, v3
	v_or_b32_e32 v34, s27, v4
	v_or_b32_e32 v40, s35, v3
	v_or_b32_e32 v38, s36, v4
	v_or_b32_e32 v44, s37, v3
	v_or_b32_e32 v42, s56, v4
	v_or_b32_e32 v48, s57, v3
	v_or_b32_e32 v46, s58, v4
	v_mad_i64_i32 v[20:21], s[8:9], v20, s13, v[12:13]
	v_mad_i64_i32 v[22:23], s[8:9], v22, s13, v[12:13]
	v_mad_i64_i32 v[24:25], s[8:9], v24, s13, v[12:13]
	v_mad_i64_i32 v[26:27], s[8:9], v26, s13, v[12:13]
	v_mad_i64_i32 v[28:29], s[8:9], v28, s13, v[12:13]
	v_mad_i64_i32 v[30:31], s[8:9], v30, s13, v[12:13]
	v_mad_i64_i32 v[32:33], s[8:9], v32, s13, v[12:13]
	v_mad_i64_i32 v[34:35], s[8:9], v34, s13, v[12:13]
	v_mad_i64_i32 v[36:37], s[8:9], v36, s13, v[12:13]
	v_mad_i64_i32 v[38:39], s[8:9], v38, s13, v[12:13]
	v_mad_i64_i32 v[40:41], s[8:9], v40, s13, v[12:13]
	v_mad_i64_i32 v[42:43], s[8:9], v42, s13, v[12:13]
	v_mad_i64_i32 v[44:45], s[8:9], v44, s13, v[12:13]
	v_mad_i64_i32 v[46:47], s[8:9], v46, s13, v[12:13]
	v_mad_i64_i32 v[48:49], s[8:9], v48, s13, v[12:13]
	global_load_dword v50, v[18:19], off
	global_load_dword v51, v[20:21], off
	global_load_dword v52, v[22:23], off
	global_load_dword v53, v[24:25], off
	global_load_dword v54, v[26:27], off
	global_load_dword v55, v[28:29], off
	global_load_dword v56, v[30:31], off
	global_load_dword v57, v[32:33], off
	global_load_dword v58, v[34:35], off
	global_load_dword v59, v[36:37], off
	global_load_dword v60, v[38:39], off
	global_load_dword v61, v[40:41], off
	global_load_dword v62, v[42:43], off
	global_load_dword v63, v[44:45], off
	global_load_dword v64, v[46:47], off
	global_load_dword v65, v[48:49], off
	v_or_b32_e32 v20, s10, v1
	v_or_b32_e32 v18, s11, v2
	s_add_i32 s6, s6, 16
	s_add_i32 s5, s5, 16
	s_add_i32 s7, s7, -16
	v_mad_u64_u32 v[18:19], s[8:9], v18, s12, v[8:9]
	v_mad_u64_u32 v[20:21], s[8:9], v20, s12, v[8:9]
	v_or_b32_e32 v19, s18, v1
	v_or_b32_e32 v21, s19, v2
	v_or_b32_e32 v28, s22, v1
	v_or_b32_e32 v26, s23, v2
	v_or_b32_e32 v32, s24, v1
	v_or_b32_e32 v30, s25, v2
	v_or_b32_e32 v36, s26, v1
	v_or_b32_e32 v34, s27, v2
	v_or_b32_e32 v40, s35, v1
	v_or_b32_e32 v38, s36, v2
	v_or_b32_e32 v44, s37, v1
	v_or_b32_e32 v42, s56, v2
	v_or_b32_e32 v48, s57, v1
	v_or_b32_e32 v46, s58, v2
	s_cmp_lg_u32 s7, 0
	v_mad_u64_u32 v[22:23], s[8:9], v21, s12, v[8:9]
	v_mad_u64_u32 v[24:25], s[8:9], v19, s12, v[8:9]
	v_mad_u64_u32 v[26:27], s[8:9], v26, s12, v[8:9]
	v_mad_u64_u32 v[28:29], s[8:9], v28, s12, v[8:9]
	v_mad_u64_u32 v[30:31], s[8:9], v30, s12, v[8:9]
	v_mad_u64_u32 v[32:33], s[8:9], v32, s12, v[8:9]
	v_mad_u64_u32 v[34:35], s[8:9], v34, s12, v[8:9]
	v_mad_u64_u32 v[36:37], s[8:9], v36, s12, v[8:9]
	v_mad_u64_u32 v[38:39], s[8:9], v38, s12, v[8:9]
	v_mad_u64_u32 v[40:41], s[8:9], v40, s12, v[8:9]
	v_mad_u64_u32 v[42:43], s[8:9], v42, s12, v[8:9]
	v_mad_u64_u32 v[44:45], s[8:9], v44, s12, v[8:9]
	v_mad_u64_u32 v[46:47], s[8:9], v46, s12, v[8:9]
	v_mad_u64_u32 v[48:49], s[8:9], v48, s12, v[8:9]
	s_waitcnt vmcnt(15)
	ds_write_b32 v18, v50
	s_waitcnt vmcnt(14)
	ds_write_b32 v20, v51
	s_waitcnt vmcnt(13)
	ds_write_b32 v22, v52
	s_waitcnt vmcnt(12)
	ds_write_b32 v24, v53
	s_waitcnt vmcnt(11)
	ds_write_b32 v26, v54
	s_waitcnt vmcnt(10)
	ds_write_b32 v28, v55
	s_waitcnt vmcnt(9)
	ds_write_b32 v30, v56
	s_waitcnt vmcnt(8)
	ds_write_b32 v32, v57
	s_waitcnt vmcnt(7)
	ds_write_b32 v34, v58
	s_waitcnt vmcnt(6)
	ds_write_b32 v36, v59
	s_waitcnt vmcnt(5)
	ds_write_b32 v38, v60
	s_waitcnt vmcnt(4)
	ds_write_b32 v40, v61
	s_waitcnt vmcnt(3)
	ds_write_b32 v42, v62
	s_waitcnt vmcnt(2)
	ds_write_b32 v44, v63
	s_waitcnt vmcnt(1)
	ds_write_b32 v46, v64
	s_waitcnt vmcnt(0)
	ds_write_b32 v48, v65
	s_cbranch_scc1 .LBB0_75
	s_waitcnt lgkmcnt(0)
	ds_read2_b32 v[12:13], v14 offset0:33 offset1:41
	ds_read2_b32 v[22:23], v14 offset1:8
	ds_read2_b32 v[24:25], v14 offset0:66 offset1:74
	ds_read2_b32 v[26:27], v14 offset0:99 offset1:107
	ds_read2_b32 v[28:29], v14 offset0:132 offset1:140
	ds_read2_b32 v[30:31], v14 offset0:165 offset1:173
	ds_read2_b32 v[32:33], v14 offset0:198 offset1:206
	ds_read2_b32 v[34:35], v14 offset0:231 offset1:239
	s_ashr_i32 s5, s4, 31
	v_lshl_add_u64 v[36:37], s[4:5], 1, v[10:11]
	v_add_lshl_u32 v4, s15, v9, 11
	s_waitcnt lgkmcnt(6)
	v_cvt_pk_bf16_f32 v18, v22, v12
	s_waitcnt lgkmcnt(4)
	v_cvt_pk_bf16_f32 v19, v24, v26
	s_waitcnt lgkmcnt(2)
	v_cvt_pk_bf16_f32 v20, v28, v30
	s_waitcnt lgkmcnt(0)
	v_cvt_pk_bf16_f32 v21, v32, v34
	v_lshl_add_u64 v[38:39], v[36:37], 0, v[4:5]
	global_store_dwordx4 v[38:39], v[18:21], off
	v_add_lshl_u32 v4, s15, v15, 11
	s_add_i32 s14, s14, s101
	v_cvt_pk_bf16_f32 v18, v23, v13
	v_cvt_pk_bf16_f32 v19, v25, v27
	v_cvt_pk_bf16_f32 v20, v29, v31
	v_cvt_pk_bf16_f32 v21, v33, v35
	ds_read2_b32 v[22:23], v14 offset0:49 offset1:57
	ds_read2_b32 v[24:25], v14 offset0:16 offset1:24
	ds_read2_b32 v[26:27], v14 offset0:82 offset1:90
	ds_read2_b32 v[28:29], v14 offset0:115 offset1:123
	ds_read2_b32 v[30:31], v14 offset0:148 offset1:156
	ds_read2_b32 v[32:33], v14 offset0:181 offset1:189
	ds_read2_b32 v[34:35], v14 offset0:214 offset1:222
	ds_read2_b32 v[38:39], v14 offset0:247 offset1:255
	v_lshl_add_u64 v[12:13], v[36:37], 0, v[4:5]
	v_add_lshl_u32 v4, s15, v16, 11
	global_store_dwordx4 v[12:13], v[18:21], off
	v_lshl_add_u64 v[12:13], v[36:37], 0, v[4:5]
	v_add_lshl_u32 v4, s15, v17, 11
	s_waitcnt lgkmcnt(6)
	v_cvt_pk_bf16_f32 v18, v24, v22
	s_waitcnt lgkmcnt(4)
	v_cvt_pk_bf16_f32 v19, v26, v28
	s_waitcnt lgkmcnt(2)
	v_cvt_pk_bf16_f32 v20, v30, v32
	s_waitcnt lgkmcnt(0)
	v_cvt_pk_bf16_f32 v21, v34, v38
	global_store_dwordx4 v[12:13], v[18:21], off
	v_lshl_add_u64 v[12:13], v[36:37], 0, v[4:5]
	s_cmpk_gt_i32 s14, 0xdff
	v_cvt_pk_bf16_f32 v18, v25, v23
	v_cvt_pk_bf16_f32 v19, v27, v29
	v_cvt_pk_bf16_f32 v20, v31, v33
	v_cvt_pk_bf16_f32 v21, v35, v39
	global_store_dwordx4 v[12:13], v[18:21], off
	s_waitcnt lgkmcnt(0)
	s_cbranch_scc0 .LBB0_48

; __global__ void __launch_bounds__(NTHR, 2) hybrid_fwd(Args a) {
	.amdhsa_kernel _Z10hybrid_fwd4Args
		.amdhsa_group_segment_fixed_size 0
		.amdhsa_private_segment_fixed_size 0
		.amdhsa_kernarg_size 400
		.amdhsa_user_sgpr_count 2
		.amdhsa_user_sgpr_dispatch_ptr 0
		.amdhsa_user_sgpr_queue_ptr 0
		.amdhsa_user_sgpr_kernarg_segment_ptr 1
		.amdhsa_user_sgpr_dispatch_id 0
		.amdhsa_user_sgpr_kernarg_preload_length 0
		.amdhsa_user_sgpr_kernarg_preload_offset 0
		.amdhsa_user_sgpr_private_segment_size 0
		.amdhsa_uses_dynamic_stack 0
		.amdhsa_enable_private_segment 0
		.amdhsa_system_sgpr_workgroup_id_x 1
		.amdhsa_system_sgpr_workgroup_id_y 0
		.amdhsa_system_sgpr_workgroup_id_z 0
		.amdhsa_system_sgpr_workgroup_info 0
		.amdhsa_system_vgpr_workitem_id 0
		.amdhsa_next_free_vgpr 254
		.amdhsa_next_free_sgpr 102
		.amdhsa_accum_offset 256
		.amdhsa_reserve_vcc 1
		.amdhsa_float_round_mode_32 0
		.amdhsa_float_round_mode_16_64 0
		.amdhsa_float_denorm_mode_32 3
		.amdhsa_float_denorm_mode_16_64 3
		.amdhsa_dx10_clamp 1
		.amdhsa_ieee_mode 1
		.amdhsa_fp16_overflow 0
		.amdhsa_tg_split 0
		.amdhsa_exception_fp_ieee_invalid_op 0
		.amdhsa_exception_fp_denorm_src 0
		.amdhsa_exception_fp_ieee_div_zero 0
		.amdhsa_exception_fp_ieee_overflow 0
		.amdhsa_exception_fp_ieee_underflow 0
		.amdhsa_exception_fp_ieee_inexact 0
		.amdhsa_exception_int_div_zero 0
	.end_amdhsa_kernel

; __global__ void __launch_bounds__(NTHR, 2) hybrid_fwd(Args a) {
amdhsa.kernels:
  - .agpr_count:     0
    .args:
      - .offset:         0
        .size:           144
        .value_kind:     by_value
      - .offset:         144
        .size:           4
        .value_kind:     hidden_block_count_x
      - .offset:         148
        .size:           4
        .value_kind:     hidden_block_count_y
      - .offset:         152
        .size:           4
        .value_kind:     hidden_block_count_z
      - .offset:         156
        .size:           2
        .value_kind:     hidden_group_size_x
      - .offset:         158
        .size:           2
        .value_kind:     hidden_group_size_y
      - .offset:         160
        .size:           2
        .value_kind:     hidden_group_size_z
      - .offset:         162
        .size:           2
        .value_kind:     hidden_remainder_x
      - .offset:         164
        .size:           2
        .value_kind:     hidden_remainder_y
      - .offset:         166
        .size:           2
        .value_kind:     hidden_remainder_z
      - .offset:         184
        .size:           8
        .value_kind:     hidden_global_offset_x
      - .offset:         192
        .size:           8
        .value_kind:     hidden_global_offset_y
      - .offset:         200
        .size:           8
        .value_kind:     hidden_global_offset_z
      - .offset:         208
        .size:           2
        .value_kind:     hidden_grid_dims
      - .offset:         264
        .size:           4
        .value_kind:     hidden_dynamic_lds_size
    .group_segment_fixed_size: 0
    .kernarg_segment_align: 8
    .kernarg_segment_size: 400
    .language:       OpenCL C
    .language_version:
      - 2
      - 0
    .max_flat_workgroup_size: 512
    .name:           _Z10hybrid_fwd4Args
    .private_segment_fixed_size: 0
    .sgpr_count:     108
    .sgpr_spill_count: 2
    .symbol:         _Z10hybrid_fwd4Args.kd
    .uniform_work_group_size: 1
    .uses_dynamic_stack: false
    .vgpr_count:     254
    .vgpr_spill_count: 0
    .wavefront_size: 64
